# v42 plus one static s_setprio 1 for waves 4-7 during the diff-attention phases (strategy 7.4)
# baseline (speedup 1.0000x reference)
; __device__ __forceinline__ unsigned xb_xcc_id() { return (unsigned)__builtin_amdgcn_s_getreg((3 << 11) | 20) & 0xFu; }
;     ...
;     if (diff && tid == 0) tk0 = atomicAdd((unsigned*)(ws + WS_CTL) + 1024 + 512 * L + 4 * rep + 64 * (int)(xb_xcc_id() & 7u), 1u);
;     if (diff) {
;         const float mq = att::wave_max(fabsf(a->in[10][j * 64 + lane])), mk = att::wave_max(fabsf(a->in[11][j * 64 + lane]));
;         M0d = 8.0f * mq * mk * att::LOG2E * 1.05f;
;         const float linit = 0.8f - 0.6f * expf(-0.3f * (float)L);
;         const float d1 = wave_sum(a->in[12][j * 64 + lane] * a->in[13][j * 64 + lane]), d2 = wave_sum(a->in[14][j * 64 + lane] * a->in[15][j * 64 + lane]);
;         lam = expf(d1) - expf(d2) + linit; omlinit = 1.0f - linit;
;     }
;     const float* subw = a->in[16] + j * 128;
;     if (diff) {
;         const int myx = (int)(xb_xcc_id() & 7u);
;         unsigned* dctr = (unsigned*)(ws + WS_CTL) + 1024 + 512 * L + 4 * rep;
;         int q = myx; bool first = true;
;         if (wave >= 4) __builtin_amdgcn_s_setprio(1);
.LBB0_787:
	s_or_b64 exec, exec, s[10:11]
	s_mov_b64 s[46:47], s[96:97]
	s_waitcnt lgkmcnt(0)
	v_mov_b32_e32 v0, v201
	s_barrier
	v_readlane_b32 s98, v252, 1
	s_nop 3
	s_cmp_ge_u32 s98, 4
	s_cbranch_scc0 .Lattn_prio_a
	s_setprio 1
.Lattn_prio_a:
	s_load_dwordx2 s[44:45], s[46:47], 0xa8
	v_and_b32_e32 v152, 63, v0
	v_or_b32_e32 v1, s86, v152
	v_mov_b32_e32 v153, 0
	v_cmp_eq_u32_e64 s[12:13], 0, v1
	s_and_saveexec_b64 s[10:11], s[12:13]
	s_cbranch_execz .LBB0_791
	s_mov_b64 s[18:19], exec
	v_mbcnt_lo_u32_b32 v1, s18, 0
	v_mbcnt_hi_u32_b32 v1, s19, v1
	s_getreg_b32 s1, hwreg(HW_REG_XCC_ID, 0, 4)
	v_cmp_eq_u32_e32 vcc, 0, v1
	s_and_saveexec_b64 s[16:17], vcc
	s_cbranch_execz .LBB0_790
	s_lshl_b32 s1, s1, 8
	s_and_b32 s1, s1, 0x700
	s_waitcnt lgkmcnt(0)
	s_add_u32 s4, s44, s1
	s_addc_u32 s5, s45, 0
	s_bcnt1_i32_b64 s1, s[18:19]
	v_mov_b32_e32 v2, 0x1000
	v_mov_b32_e32 v3, s1
	global_atomic_add v2, v2, v3, s[4:5] offset:2048 sc0

; __device__ __forceinline__ unsigned xb_ld(unsigned* p)              { return __hip_atomic_load(p, __ATOMIC_RELAXED, __HIP_MEMORY_SCOPE_AGENT); }
; __device__ __forceinline__ unsigned xb_add(unsigned* p, unsigned v) { return __hip_atomic_fetch_add(p, v, __ATOMIC_RELAXED, __HIP_MEMORY_SCOPE_AGENT); }
; __device__ __forceinline__ void xcd_barrier_complete(unsigned* bar, unsigned x, unsigned& nloc, unsigned& nx) {
;     const unsigned G = gridDim.x * gridDim.y * gridDim.z;
;     unsigned sum, cnt, mine, sp = 0u;
;     for (;;) {
;         sum = 0u; cnt = 0u; mine = 0u;
; #pragma unroll
;         for (unsigned j = 0; j < 16; ++j) { const unsigned c = xb_ld(&bar[XB_XCNT(j)]); sum += c; cnt += (c > 0u) ? 1u : 0u; mine = (j == x) ? c : mine; }
; __device__ __forceinline__ void xcd_barrier(const XcdBarrier& b) {
;     asm volatile("s_waitcnt vmcnt(0)" ::: "memory");
;     __syncthreads();
;     if (b.leader) {
;         unsigned* bar = b.bar;
;         __builtin_amdgcn_s_waitcnt(0);
;         unsigned nloc = b.st[0], nx = b.st[1];
;         if (nloc == 0u) { xcd_barrier_complete(bar, b.x, nloc, nx); b.st[0] = nloc; b.st[1] = nx; }
;         const unsigned old = xb_add(&bar[XB_XSUB(b.x)], 1u);
.LBB0_841:
	s_setprio 0
	v_readlane_b32 s16, v252, 15
	v_readlane_b32 s17, v252, 16
	s_getreg_b32 s0, hwreg(HW_REG_XCC_ID, 0, 4)
	s_waitcnt vmcnt(0)
	v_readlane_b32 s4, v252, 3
	v_readlane_b32 s5, v252, 4
	s_barrier
	s_and_saveexec_b64 s[12:13], s[4:5]
	s_cbranch_execz .LBB0_893
	s_add_i32 s3, 0, 0x20040
	v_mov_b32_e32 v0, s3
	s_load_dwordx2 s[16:17], s[16:17], 0xa8
	s_waitcnt vmcnt(0) expcnt(0) lgkmcnt(0)
	ds_read_b32 v2, v0
	s_add_i32 s3, 0, 0x20044
	v_mov_b32_e32 v0, s3
	ds_read_b32 v0, v0
	s_and_b32 s0, s0, 15
	s_waitcnt lgkmcnt(1)
	v_cmp_ne_u32_e32 vcc, 0, v2
	s_cbranch_vccnz .LBB0_857
	s_add_u32 s18, s16, 0x4200
	s_addc_u32 s19, s17, 0
	s_add_u32 s20, s16, 0x4400
	s_addc_u32 s21, s17, 0
	s_add_u32 s22, s16, 0x4500
	s_addc_u32 s23, s17, 0
	s_add_u32 s24, s16, 0x4600
	s_addc_u32 s25, s17, 0
	s_add_u32 s26, s16, 0x4700
	s_addc_u32 s27, s17, 0
	s_add_u32 s44, s16, 0x4800
	s_addc_u32 s45, s17, 0
	s_add_u32 s46, s16, 0x4900
	s_addc_u32 s47, s17, 0
	s_add_u32 s48, s16, 0x4a00
	s_addc_u32 s49, s17, 0
	s_add_u32 s50, s16, 0x4b00
	s_addc_u32 s51, s17, 0
	s_add_u32 s52, s16, 0x4c00
	s_addc_u32 s53, s17, 0
	s_add_u32 s54, s16, 0x4d00
	s_addc_u32 s55, s17, 0
	s_add_u32 s56, s16, 0x4e00
	s_addc_u32 s57, s17, 0
	s_add_u32 s58, s16, 0x4f00
	s_addc_u32 s59, s17, 0
	s_add_u32 s60, s16, 0x5000
	s_addc_u32 s61, s17, 0
	s_add_u32 s62, s16, 0x5100
	s_addc_u32 s63, s17, 0
	s_add_u32 s64, s16, 0x5200
	v_readlane_b32 s3, v252, 0
	s_addc_u32 s65, s17, 0
	s_mul_i32 s3, s29, s3
	s_add_u32 s66, s16, 0x5300
	s_mul_i32 s3, s3, s28
	s_addc_u32 s67, s17, 0
	s_mov_b32 s33, 1
	v_mov_b32_e32 v16, 0
	s_branch .LBB0_845

; __device__ __forceinline__ unsigned xb_xcc_id() { return (unsigned)__builtin_amdgcn_s_getreg((3 << 11) | 20) & 0xFu; }
;     ...
;     if (diff && tid == 0) tk0 = atomicAdd((unsigned*)(ws + WS_CTL) + 1024 + 512 * L + 4 * rep + 64 * (int)(xb_xcc_id() & 7u), 1u);
;     if (diff) {
;         const float mq = att::wave_max(fabsf(a->in[10][j * 64 + lane])), mk = att::wave_max(fabsf(a->in[11][j * 64 + lane]));
;         M0d = 8.0f * mq * mk * att::LOG2E * 1.05f;
;         const float linit = 0.8f - 0.6f * expf(-0.3f * (float)L);
;         const float d1 = wave_sum(a->in[12][j * 64 + lane] * a->in[13][j * 64 + lane]), d2 = wave_sum(a->in[14][j * 64 + lane] * a->in[15][j * 64 + lane]);
;         lam = expf(d1) - expf(d2) + linit; omlinit = 1.0f - linit;
;     }
;     const float* subw = a->in[16] + j * 128;
;     if (diff) {
;         const int myx = (int)(xb_xcc_id() & 7u);
;         unsigned* dctr = (unsigned*)(ws + WS_CTL) + 1024 + 512 * L + 4 * rep;
;         int q = myx; bool first = true;
;         if (wave >= 4) __builtin_amdgcn_s_setprio(1);
.LBB0_1831:
	s_or_b64 exec, exec, s[6:7]
	v_readlane_b32 s44, v252, 15
	v_readlane_b32 s45, v252, 16
	s_waitcnt lgkmcnt(0)
	v_mov_b32_e32 v0, v201
	s_barrier
	v_readlane_b32 s98, v252, 1
	s_nop 3
	s_cmp_ge_u32 s98, 4
	s_cbranch_scc0 .Lattn_prio_b
	s_setprio 1
.Lattn_prio_b:
	s_load_dwordx2 s[42:43], s[44:45], 0xa8
	v_and_b32_e32 v152, 63, v0
	v_readlane_b32 s0, v252, 1
	v_mov_b32_e32 v153, 0
	s_nop 0
	v_or_b32_e32 v1, s0, v152
	v_cmp_eq_u32_e64 s[6:7], 0, v1
	s_and_saveexec_b64 s[8:9], s[6:7]
	s_cbranch_execz .LBB0_1835
	s_mov_b64 s[16:17], exec
	v_mbcnt_lo_u32_b32 v1, s16, 0
	v_mbcnt_hi_u32_b32 v1, s17, v1
	s_getreg_b32 s0, hwreg(HW_REG_XCC_ID, 0, 4)
	v_cmp_eq_u32_e32 vcc, 0, v1
	s_and_saveexec_b64 s[14:15], vcc
	s_cbranch_execz .LBB0_1834
	s_lshl_b32 s0, s0, 8
	s_and_b32 s0, s0, 0x700
	s_waitcnt lgkmcnt(0)
	s_add_u32 s12, s42, s0
	s_addc_u32 s13, s43, 0
	s_bcnt1_i32_b64 s0, s[16:17]
	v_mov_b32_e32 v2, 0x2000
	v_mov_b32_e32 v3, s0
	global_atomic_add v2, v2, v3, s[12:13] offset:2048 sc0

; __device__ __forceinline__ unsigned xb_ld(unsigned* p)              { return __hip_atomic_load(p, __ATOMIC_RELAXED, __HIP_MEMORY_SCOPE_AGENT); }
; __device__ __forceinline__ unsigned xb_add(unsigned* p, unsigned v) { return __hip_atomic_fetch_add(p, v, __ATOMIC_RELAXED, __HIP_MEMORY_SCOPE_AGENT); }
; __device__ __forceinline__ void xcd_barrier_complete(unsigned* bar, unsigned x, unsigned& nloc, unsigned& nx) {
;     const unsigned G = gridDim.x * gridDim.y * gridDim.z;
;     unsigned sum, cnt, mine, sp = 0u;
;     for (;;) {
;         sum = 0u; cnt = 0u; mine = 0u;
; #pragma unroll
;         for (unsigned j = 0; j < 16; ++j) { const unsigned c = xb_ld(&bar[XB_XCNT(j)]); sum += c; cnt += (c > 0u) ? 1u : 0u; mine = (j == x) ? c : mine; }
; __device__ __forceinline__ void xcd_barrier(const XcdBarrier& b) {
;     asm volatile("s_waitcnt vmcnt(0)" ::: "memory");
;     __syncthreads();
;     if (b.leader) {
;         unsigned* bar = b.bar;
;         __builtin_amdgcn_s_waitcnt(0);
;         unsigned nloc = b.st[0], nx = b.st[1];
;         if (nloc == 0u) { xcd_barrier_complete(bar, b.x, nloc, nx); b.st[0] = nloc; b.st[1] = nx; }
;         const unsigned old = xb_add(&bar[XB_XSUB(b.x)], 1u);
.LBB0_1885:
	s_setprio 0
	v_readlane_b32 s62, v252, 15
	v_readlane_b32 s63, v252, 16
	s_mov_b64 s[8:9], s[62:63]
	s_getreg_b32 s0, hwreg(HW_REG_XCC_ID, 0, 4)
	s_waitcnt vmcnt(0)
	s_barrier
	s_mov_b64 s[6:7], exec
	v_readlane_b32 s4, v252, 3
	v_readlane_b32 s5, v252, 4
	s_and_b64 s[4:5], s[6:7], s[4:5]
	s_mov_b64 exec, s[4:5]
	s_cbranch_execz .LBB0_1937
	s_add_i32 s1, 0, 0x20040
	v_mov_b32_e32 v0, s1
	s_load_dwordx2 s[8:9], s[8:9], 0xa8
	s_waitcnt vmcnt(0) expcnt(0) lgkmcnt(0)
	ds_read_b32 v2, v0
	s_add_i32 s1, 0, 0x20044
	v_mov_b32_e32 v0, s1
	ds_read_b32 v0, v0
	s_and_b32 s0, s0, 15
	s_waitcnt lgkmcnt(1)
	v_cmp_ne_u32_e32 vcc, 0, v2
	s_cbranch_vccnz .LBB0_1901
	s_add_u32 s10, s8, 0x4200
	s_addc_u32 s11, s9, 0
	s_add_u32 s14, s8, 0x4400
	s_addc_u32 s15, s9, 0
	s_add_u32 s16, s8, 0x4500
	s_addc_u32 s17, s9, 0
	s_add_u32 s18, s8, 0x4600
	s_addc_u32 s19, s9, 0
	s_add_u32 s20, s8, 0x4700
	s_addc_u32 s21, s9, 0
	s_add_u32 s22, s8, 0x4800
	s_addc_u32 s23, s9, 0
	s_add_u32 s24, s8, 0x4900
	s_addc_u32 s25, s9, 0
	s_add_u32 s26, s8, 0x4a00
	s_addc_u32 s27, s9, 0
	s_add_u32 s34, s8, 0x4b00
	s_addc_u32 s35, s9, 0
	s_add_u32 s36, s8, 0x4c00
	s_addc_u32 s37, s9, 0
	s_add_u32 s38, s8, 0x4d00
	s_addc_u32 s39, s9, 0
	s_add_u32 s40, s8, 0x4e00
	s_addc_u32 s41, s9, 0
	s_add_u32 s42, s8, 0x4f00
	s_addc_u32 s43, s9, 0
	s_add_u32 s44, s8, 0x5000
	s_addc_u32 s45, s9, 0
	s_add_u32 s46, s8, 0x5100
	s_addc_u32 s47, s9, 0
	s_add_u32 s48, s8, 0x5200
	v_readlane_b32 s1, v252, 0
	s_addc_u32 s49, s9, 0
	s_mul_i32 s1, s29, s1
	s_add_u32 s50, s8, 0x5300
	s_mul_i32 s1, s1, s28
	s_addc_u32 s51, s9, 0
	s_mov_b32 s3, 1
	v_mov_b32_e32 v16, 0
	s_branch .LBB0_1889
